# baseline (speedup 1.0000x reference)
; DEVI void phase_e(const Params& p, const Pass& ps, char* shm, const int wid_s_) {
;     ...
;   const int nqb = ps.S >> 8, items = ps.nb * 16 * nqb, per = gridDim.x >> 3, xcd = blockIdx.x & 7, slot = blockIdx.x >> 3;
;   const int NT = ps.Lpad >> 6;
;   for (int it = 0;; ++it) {
;     int item = (it * 8 + xcd) * per + slot; if (item >= items) break;
;     int qb = item % nqb, bh = item / nqb, h = bh & 15, b = bh >> 4;
.LBB0_977:
	s_or_b64 exec, exec, s[6:7]
	s_lshr_b32 s1, s29, 8
	s_mul_i32 s2, s22, s1
	s_lshl_b32 s55, s2, 4
	s_cmp_ge_u32 s34, s55
	s_barrier
	s_cbranch_scc1 .LBB0_998
	s_lshr_b32 s4, s28, 6
	s_lshl_b32 s5, s28, 1
	s_add_i32 s31, s1, -1
	s_ff1_i32_b32 s93, s1
	s_lshl_b32 s64, s28, 1
	s_mov_b32 s12, 0
	s_mov_b32 s1, s34
	s_mov_b32 s34, 0
	v_readfirstlane_b32 s100, v207
	s_lshr_b32 s100, s100, 6
	s_cmp_ge_u32 s100, 4
	s_cbranch_scc1 .Lprio_skip
	s_setprio 1
